# norm_phase (layer 0): touch-prefetch the iteration's 4 rows with dword loads before the serial load-wait chain
# baseline (speedup 1.0000x reference)
.LBB0_17:
	v_add_co_u32_e32 v30, vcc, 0xffffd000, v38
	v_add_u32_e32 v34, s84, v34
	s_nop 0
	v_addc_co_u32_e32 v31, vcc, -1, v39, vcc
	global_load_dword v212, v[30:31], off offset:-1032
	global_load_dword v212, v[30:31], off offset:-8
	v_add_co_u32_e32 v214, vcc, s2, v38
	s_nop 1
	v_addc_co_u32_e32 v215, vcc, -1, v39, vcc
	global_load_dword v212, v[214:215], off offset:-3080
	global_load_dword v212, v[214:215], off offset:-2056
	global_load_dword v212, v[214:215], off offset:-1032
	global_load_dword v212, v[214:215], off offset:-8
	v_add_co_u32_e32 v216, vcc, s21, v38
	s_nop 1
	v_addc_co_u32_e32 v217, vcc, -1, v39, vcc
	global_load_dword v212, v[216:217], off offset:-3080
	global_load_dword v212, v[216:217], off offset:-2056
	global_load_dword v212, v[216:217], off offset:-1032
	global_load_dword v212, v[216:217], off offset:-8
	global_load_dword v212, v[38:39], off offset:-3080
	global_load_dword v212, v[38:39], off offset:-2056
	global_load_dword v212, v[38:39], off offset:-1032
	global_load_dword v212, v[38:39], off offset:-8
	global_load_dwordx4 v[18:21], v[30:31], off offset:-3080
	global_load_dwordx4 v[22:25], v[30:31], off offset:-2056
	v_add_co_u32_e32 v60, vcc, s2, v38
	s_waitcnt vmcnt(1)
	v_mov_b32_e32 v40, v19
	s_waitcnt vmcnt(0)
	v_mov_b32_e32 v41, v23
	v_mov_b32_e32 v32, v18
	v_mov_b32_e32 v33, v22
	v_pk_mul_f32 v[40:41], v[40:41], v[40:41]
	v_mov_b32_e32 v26, v20
	v_mov_b32_e32 v27, v24
	v_pk_fma_f32 v[32:33], v[32:33], v[32:33], v[40:41]
	v_mov_b32_e32 v28, v21
	v_mov_b32_e32 v29, v25
	v_pk_fma_f32 v[26:27], v[26:27], v[26:27], v[32:33]
	v_addc_co_u32_e32 v61, vcc, -1, v39, vcc
	v_pk_fma_f32 v[40:41], v[28:29], v[28:29], v[26:27]
	global_load_dwordx4 v[26:29], v[30:31], off offset:-1032
	s_nop 0
	global_load_dwordx4 v[30:33], v[30:31], off offset:-8
	s_waitcnt vmcnt(1)
	v_mov_b32_e32 v54, v27
	s_waitcnt vmcnt(0)
	v_mov_b32_e32 v55, v31
	v_mov_b32_e32 v52, v26
	v_mov_b32_e32 v53, v30
	v_pk_mul_f32 v[54:55], v[54:55], v[54:55]
	v_mov_b32_e32 v42, v28
	v_mov_b32_e32 v43, v32
	v_pk_fma_f32 v[52:53], v[52:53], v[52:53], v[54:55]
	v_mov_b32_e32 v44, v29
	v_mov_b32_e32 v45, v33
	v_pk_fma_f32 v[42:43], v[42:43], v[42:43], v[52:53]
	s_nop 0
	v_pk_fma_f32 v[64:65], v[44:45], v[44:45], v[42:43]
	global_load_dwordx4 v[42:45], v[60:61], off offset:-3080
	global_load_dwordx4 v[52:55], v[60:61], off offset:-2056
	s_waitcnt vmcnt(1)
	v_mov_b32_e32 v66, v43
	s_waitcnt vmcnt(0)
	v_mov_b32_e32 v67, v53
	v_mov_b32_e32 v62, v42
	v_mov_b32_e32 v63, v52
	v_pk_mul_f32 v[66:67], v[66:67], v[66:67]
	v_mov_b32_e32 v56, v44
	v_mov_b32_e32 v57, v54
	v_pk_fma_f32 v[62:63], v[62:63], v[62:63], v[66:67]
	v_mov_b32_e32 v58, v45
	v_mov_b32_e32 v59, v55
	v_pk_fma_f32 v[56:57], v[56:57], v[56:57], v[62:63]
	s_nop 0
	v_pk_fma_f32 v[66:67], v[58:59], v[58:59], v[56:57]
	global_load_dwordx4 v[56:59], v[60:61], off offset:-1032
	s_nop 0
	global_load_dwordx4 v[60:63], v[60:61], off offset:-8
	s_waitcnt vmcnt(1)
	v_mov_b32_e32 v74, v57
	s_waitcnt vmcnt(0)
	v_mov_b32_e32 v75, v61
	v_mov_b32_e32 v72, v56
	v_mov_b32_e32 v73, v60
	v_pk_mul_f32 v[74:75], v[74:75], v[74:75]
	v_mov_b32_e32 v68, v58
	v_mov_b32_e32 v69, v62
	v_pk_fma_f32 v[72:73], v[72:73], v[72:73], v[74:75]
	v_mov_b32_e32 v70, v59
	v_mov_b32_e32 v71, v63
	v_pk_fma_f32 v[68:69], v[68:69], v[68:69], v[72:73]
	s_nop 0
	v_pk_fma_f32 v[68:69], v[70:71], v[70:71], v[68:69]
	v_mov_b32_e32 v70, v66
	v_mov_b32_e32 v71, v40
	v_mov_b32_e32 v40, v67
	v_pk_add_f32 v[40:41], v[70:71], v[40:41]
	v_mov_b32_e32 v66, v68
	v_mov_b32_e32 v67, v64
	v_pk_add_f32 v[40:41], v[40:41], v[66:67]
	v_mov_b32_e32 v64, v69
	v_pk_add_f32 v[40:41], v[40:41], v[64:65]
	ds_bpermute_b32 v65, v0, v41
	ds_bpermute_b32 v64, v0, v40
	s_waitcnt lgkmcnt(0)
	v_pk_add_f32 v[40:41], v[40:41], v[64:65]
	ds_bpermute_b32 v65, v46, v41
	ds_bpermute_b32 v64, v46, v40
	s_waitcnt lgkmcnt(0)
	v_pk_add_f32 v[40:41], v[40:41], v[64:65]
	ds_bpermute_b32 v65, v47, v41
	ds_bpermute_b32 v64, v47, v40
	s_waitcnt lgkmcnt(0)
	v_pk_add_f32 v[40:41], v[40:41], v[64:65]
	ds_bpermute_b32 v65, v48, v41
	ds_bpermute_b32 v64, v48, v40
	s_waitcnt lgkmcnt(0)
	v_pk_add_f32 v[40:41], v[40:41], v[64:65]
	ds_bpermute_b32 v65, v49, v41
	ds_bpermute_b32 v64, v49, v40
	s_waitcnt lgkmcnt(0)
	v_pk_add_f32 v[40:41], v[40:41], v[64:65]
	ds_bpermute_b32 v65, v50, v41
	ds_bpermute_b32 v64, v50, v40
	s_waitcnt lgkmcnt(0)
	v_pk_add_f32 v[64:65], v[40:41], v[64:65]
	v_mov_b64_e32 v[40:41], s[20:21]
	v_pk_fma_f32 v[64:65], v[64:65], s[14:15], v[40:41] op_sel_hi:[1,0,0]
	s_nop 0
	v_mul_f32_e32 v35, 0x4b800000, v65
	v_cmp_gt_f32_e64 s[0:1], s15, v65
	v_cmp_gt_f32_e32 vcc, s15, v64
	s_nop 0
	v_cndmask_b32_e64 v35, v65, v35, s[0:1]
	v_rsq_f32_e32 v35, v35
	s_nop 0
	v_mul_f32_e32 v51, 0x45800000, v35
	v_cndmask_b32_e64 v66, v35, v51, s[0:1]
	v_pk_mul_f32 v[18:19], v[18:19], v[66:67] op_sel_hi:[1,0]
	v_pk_mul_f32 v[20:21], v[20:21], v[66:67] op_sel_hi:[1,0]
	v_pk_mul_f32 v[18:19], v[2:3], v[18:19]
	v_pk_mul_f32 v[20:21], v[4:5], v[20:21]
	v_cvt_pk_bf16_f32 v18, v18, v19
	v_cvt_pk_bf16_f32 v19, v20, v21
	v_add_co_u32_e64 v20, s[0:1], s21, v36
	s_nop 1
	v_addc_co_u32_e64 v21, s[0:1], -1, v37, s[0:1]
	global_store_dwordx2 v[20:21], v[18:19], off offset:-3588
	v_pk_mul_f32 v[18:19], v[22:23], v[66:67] op_sel_hi:[1,0]
	v_pk_mul_f32 v[22:23], v[24:25], v[66:67] op_sel_hi:[1,0]
	v_pk_mul_f32 v[18:19], v[6:7], v[18:19]
	v_pk_mul_f32 v[22:23], v[8:9], v[22:23]
	v_cvt_pk_bf16_f32 v18, v18, v19
	v_cvt_pk_bf16_f32 v19, v22, v23
	global_store_dwordx2 v[20:21], v[18:19], off offset:-3076
	v_pk_mul_f32 v[18:19], v[26:27], v[66:67] op_sel_hi:[1,0]
	v_pk_mul_f32 v[22:23], v[28:29], v[66:67] op_sel_hi:[1,0]
	v_pk_mul_f32 v[18:19], v[10:11], v[18:19]
	v_pk_mul_f32 v[22:23], v[12:13], v[22:23]
	v_cvt_pk_bf16_f32 v18, v18, v19
	v_cvt_pk_bf16_f32 v19, v22, v23
	global_store_dwordx2 v[20:21], v[18:19], off offset:-2564
	v_pk_mul_f32 v[18:19], v[30:31], v[66:67] op_sel_hi:[1,0]
	v_pk_mul_f32 v[22:23], v[32:33], v[66:67] op_sel_hi:[1,0]
	v_pk_mul_f32 v[18:19], v[14:15], v[18:19]
	v_pk_mul_f32 v[22:23], v[16:17], v[22:23]
	v_cvt_pk_bf16_f32 v18, v18, v19
	v_cvt_pk_bf16_f32 v19, v22, v23
	global_store_dwordx2 v[20:21], v[18:19], off offset:-2052
	v_mul_f32_e32 v18, 0x4b800000, v64
	v_cndmask_b32_e32 v18, v64, v18, vcc
	v_rsq_f32_e32 v18, v18
	s_nop 0
	v_mul_f32_e32 v19, 0x45800000, v18
	v_cndmask_b32_e32 v18, v18, v19, vcc
	v_pk_mul_f32 v[22:23], v[42:43], v[18:19] op_sel_hi:[1,0]
	v_pk_mul_f32 v[24:25], v[44:45], v[18:19] op_sel_hi:[1,0]
	v_pk_mul_f32 v[22:23], v[2:3], v[22:23]
	v_pk_mul_f32 v[24:25], v[4:5], v[24:25]
	v_cvt_pk_bf16_f32 v22, v22, v23
	v_cvt_pk_bf16_f32 v23, v24, v25
	global_store_dwordx2 v[20:21], v[22:23], off offset:-1540
	v_pk_mul_f32 v[22:23], v[52:53], v[18:19] op_sel_hi:[1,0]
	v_pk_mul_f32 v[24:25], v[54:55], v[18:19] op_sel_hi:[1,0]
	v_pk_mul_f32 v[22:23], v[6:7], v[22:23]
	v_pk_mul_f32 v[24:25], v[8:9], v[24:25]
	v_cvt_pk_bf16_f32 v22, v22, v23
	v_cvt_pk_bf16_f32 v23, v24, v25
	global_store_dwordx2 v[20:21], v[22:23], off offset:-1028
	v_pk_mul_f32 v[22:23], v[56:57], v[18:19] op_sel_hi:[1,0]
	v_pk_mul_f32 v[24:25], v[58:59], v[18:19] op_sel_hi:[1,0]
	v_pk_mul_f32 v[22:23], v[10:11], v[22:23]
	v_pk_mul_f32 v[24:25], v[12:13], v[24:25]
	v_cvt_pk_bf16_f32 v22, v22, v23
	v_cvt_pk_bf16_f32 v23, v24, v25
	global_store_dwordx2 v[20:21], v[22:23], off offset:-516
	v_pk_mul_f32 v[22:23], v[60:61], v[18:19] op_sel_hi:[1,0]
	v_pk_mul_f32 v[18:19], v[62:63], v[18:19] op_sel_hi:[1,0]
	v_pk_mul_f32 v[22:23], v[14:15], v[22:23]
	v_pk_mul_f32 v[18:19], v[16:17], v[18:19]
	v_cvt_pk_bf16_f32 v22, v22, v23
	v_cvt_pk_bf16_f32 v23, v18, v19
	global_store_dwordx2 v[20:21], v[22:23], off offset:-4
	v_add_co_u32_e32 v22, vcc, s21, v38
	s_nop 1
	v_addc_co_u32_e32 v23, vcc, -1, v39, vcc
	global_load_dwordx4 v[26:29], v[22:23], off offset:-3080
	global_load_dwordx4 v[18:21], v[22:23], off offset:-2056
	s_waitcnt vmcnt(1)
	v_mov_b32_e32 v42, v27
	s_waitcnt vmcnt(0)
	v_mov_b32_e32 v43, v19
	v_mov_b32_e32 v32, v26
	v_mov_b32_e32 v33, v18
	v_pk_mul_f32 v[42:43], v[42:43], v[42:43]
	v_mov_b32_e32 v24, v28
	v_mov_b32_e32 v25, v20
	v_pk_fma_f32 v[32:33], v[32:33], v[32:33], v[42:43]
	v_mov_b32_e32 v30, v29
	v_mov_b32_e32 v31, v21
	v_pk_fma_f32 v[24:25], v[24:25], v[24:25], v[32:33]
	s_nop 0
	v_pk_fma_f32 v[42:43], v[30:31], v[30:31], v[24:25]
	global_load_dwordx4 v[30:33], v[22:23], off offset:-1032
	s_nop 0
	global_load_dwordx4 v[22:25], v[22:23], off offset:-8
	s_waitcnt vmcnt(1)
	v_mov_b32_e32 v56, v31
	s_waitcnt vmcnt(0)
	v_mov_b32_e32 v57, v23
	v_mov_b32_e32 v54, v30
	v_mov_b32_e32 v55, v22
	v_pk_mul_f32 v[56:57], v[56:57], v[56:57]
	v_mov_b32_e32 v44, v32
	v_mov_b32_e32 v45, v24
	v_pk_fma_f32 v[54:55], v[54:55], v[54:55], v[56:57]
	v_mov_b32_e32 v52, v33
	v_mov_b32_e32 v53, v25
	v_pk_fma_f32 v[44:45], v[44:45], v[44:45], v[54:55]
	s_nop 0
	v_pk_fma_f32 v[44:45], v[52:53], v[52:53], v[44:45]
	global_load_dwordx4 v[52:55], v[38:39], off offset:-3080
	global_load_dwordx4 v[56:59], v[38:39], off offset:-2056
	s_waitcnt vmcnt(1)
	v_mov_b32_e32 v66, v53
	s_waitcnt vmcnt(0)
	v_mov_b32_e32 v67, v57
	v_mov_b32_e32 v64, v52
	v_mov_b32_e32 v65, v56
	v_pk_mul_f32 v[66:67], v[66:67], v[66:67]
	v_mov_b32_e32 v60, v54
	v_mov_b32_e32 v61, v58
	v_pk_fma_f32 v[64:65], v[64:65], v[64:65], v[66:67]
	v_mov_b32_e32 v62, v55
	v_mov_b32_e32 v63, v59
	v_pk_fma_f32 v[60:61], v[60:61], v[60:61], v[64:65]
	s_nop 0
	v_pk_fma_f32 v[68:69], v[62:63], v[62:63], v[60:61]
	global_load_dwordx4 v[60:63], v[38:39], off offset:-1032
	global_load_dwordx4 v[64:67], v[38:39], off offset:-8
	v_lshl_add_u64 v[38:39], v[38:39], 0, s[12:13]
	s_waitcnt vmcnt(1)
	v_mov_b32_e32 v76, v61
	s_waitcnt vmcnt(0)
	v_mov_b32_e32 v77, v65
	v_mov_b32_e32 v74, v60
	v_mov_b32_e32 v75, v64
	v_pk_mul_f32 v[76:77], v[76:77], v[76:77]
	v_mov_b32_e32 v70, v62
	v_mov_b32_e32 v71, v66
	v_pk_fma_f32 v[74:75], v[74:75], v[74:75], v[76:77]
	v_mov_b32_e32 v72, v63
	v_mov_b32_e32 v73, v67
	v_pk_fma_f32 v[70:71], v[70:71], v[70:71], v[74:75]
	s_nop 0
	v_pk_fma_f32 v[70:71], v[72:73], v[72:73], v[70:71]
	v_mov_b32_e32 v72, v68
	v_mov_b32_e32 v73, v42
	v_mov_b32_e32 v42, v69
	v_pk_add_f32 v[42:43], v[72:73], v[42:43]
	v_mov_b32_e32 v68, v70
	v_mov_b32_e32 v69, v44
	v_pk_add_f32 v[42:43], v[42:43], v[68:69]
	v_mov_b32_e32 v44, v71
	v_pk_add_f32 v[42:43], v[42:43], v[44:45]
	ds_bpermute_b32 v45, v0, v43
	ds_bpermute_b32 v44, v0, v42
	s_waitcnt lgkmcnt(0)
	v_pk_add_f32 v[42:43], v[42:43], v[44:45]
	ds_bpermute_b32 v45, v46, v43
	ds_bpermute_b32 v44, v46, v42
	s_waitcnt lgkmcnt(0)
	v_pk_add_f32 v[42:43], v[42:43], v[44:45]
	ds_bpermute_b32 v45, v47, v43
	ds_bpermute_b32 v44, v47, v42
	s_waitcnt lgkmcnt(0)
	v_pk_add_f32 v[42:43], v[42:43], v[44:45]
	ds_bpermute_b32 v45, v48, v43
	ds_bpermute_b32 v44, v48, v42
	s_waitcnt lgkmcnt(0)
	v_pk_add_f32 v[42:43], v[42:43], v[44:45]
	ds_bpermute_b32 v45, v49, v43
	ds_bpermute_b32 v44, v49, v42
	s_waitcnt lgkmcnt(0)
	v_pk_add_f32 v[42:43], v[42:43], v[44:45]
	ds_bpermute_b32 v45, v50, v43
	ds_bpermute_b32 v44, v50, v42
	s_waitcnt lgkmcnt(0)
	v_pk_add_f32 v[42:43], v[42:43], v[44:45]
	s_nop 0
	v_pk_fma_f32 v[40:41], v[42:43], s[14:15], v[40:41] op_sel_hi:[1,0,0]
	s_nop 0
	v_mul_f32_e32 v35, 0x4b800000, v41
	v_cmp_gt_f32_e64 s[0:1], s15, v41
	v_cmp_gt_f32_e32 vcc, s15, v40
	s_nop 0
	v_cndmask_b32_e64 v35, v41, v35, s[0:1]
	v_rsq_f32_e32 v35, v35
	s_nop 0
	v_mul_f32_e32 v41, 0x45800000, v35
	v_cndmask_b32_e64 v42, v35, v41, s[0:1]
	v_pk_mul_f32 v[18:19], v[18:19], v[42:43] op_sel_hi:[1,0]
	v_pk_mul_f32 v[20:21], v[20:21], v[42:43] op_sel_hi:[1,0]
	v_pk_mul_f32 v[18:19], v[6:7], v[18:19]
	v_pk_mul_f32 v[20:21], v[8:9], v[20:21]
	v_cvt_pk_bf16_f32 v18, v18, v19
	v_cvt_pk_bf16_f32 v19, v20, v21
	global_store_dwordx2 v[36:37], v[18:19], off offset:-3076
	v_pk_mul_f32 v[18:19], v[30:31], v[42:43] op_sel_hi:[1,0]
	v_pk_mul_f32 v[20:21], v[32:33], v[42:43] op_sel_hi:[1,0]
	v_pk_mul_f32 v[18:19], v[10:11], v[18:19]
	v_pk_mul_f32 v[20:21], v[12:13], v[20:21]
	v_cvt_pk_bf16_f32 v18, v18, v19
	v_cvt_pk_bf16_f32 v19, v20, v21
	global_store_dwordx2 v[36:37], v[18:19], off offset:-2564
	v_pk_mul_f32 v[18:19], v[22:23], v[42:43] op_sel_hi:[1,0]
	v_pk_mul_f32 v[20:21], v[24:25], v[42:43] op_sel_hi:[1,0]
	v_pk_mul_f32 v[18:19], v[14:15], v[18:19]
	v_pk_mul_f32 v[20:21], v[16:17], v[20:21]
	v_cvt_pk_bf16_f32 v18, v18, v19
	v_cvt_pk_bf16_f32 v19, v20, v21
	global_store_dwordx2 v[36:37], v[18:19], off offset:-2052
	v_mul_f32_e32 v18, 0x4b800000, v40
	v_cndmask_b32_e32 v18, v40, v18, vcc
	v_rsq_f32_e32 v18, v18
	v_pk_mul_f32 v[26:27], v[26:27], v[42:43] op_sel_hi:[1,0]
	v_pk_mul_f32 v[28:29], v[28:29], v[42:43] op_sel_hi:[1,0]
	v_pk_mul_f32 v[26:27], v[2:3], v[26:27]
	v_mul_f32_e32 v19, 0x45800000, v18
	v_cndmask_b32_e32 v18, v18, v19, vcc
	v_pk_mul_f32 v[20:21], v[52:53], v[18:19] op_sel_hi:[1,0]
	v_pk_mul_f32 v[22:23], v[54:55], v[18:19] op_sel_hi:[1,0]
	v_pk_mul_f32 v[20:21], v[2:3], v[20:21]
	v_pk_mul_f32 v[22:23], v[4:5], v[22:23]
	v_cvt_pk_bf16_f32 v20, v20, v21
	v_cvt_pk_bf16_f32 v21, v22, v23
	global_store_dwordx2 v[36:37], v[20:21], off offset:-1540
	v_pk_mul_f32 v[20:21], v[56:57], v[18:19] op_sel_hi:[1,0]
	v_pk_mul_f32 v[22:23], v[58:59], v[18:19] op_sel_hi:[1,0]
	v_pk_mul_f32 v[20:21], v[6:7], v[20:21]
	v_pk_mul_f32 v[22:23], v[8:9], v[22:23]
	v_cvt_pk_bf16_f32 v20, v20, v21
	v_cvt_pk_bf16_f32 v21, v22, v23
	global_store_dwordx2 v[36:37], v[20:21], off offset:-1028
	v_pk_mul_f32 v[20:21], v[60:61], v[18:19] op_sel_hi:[1,0]
	v_pk_mul_f32 v[22:23], v[62:63], v[18:19] op_sel_hi:[1,0]
	v_pk_mul_f32 v[20:21], v[10:11], v[20:21]
	v_pk_mul_f32 v[22:23], v[12:13], v[22:23]
	v_cvt_pk_bf16_f32 v20, v20, v21
	v_cvt_pk_bf16_f32 v21, v22, v23
	global_store_dwordx2 v[36:37], v[20:21], off offset:-516
	v_pk_mul_f32 v[20:21], v[64:65], v[18:19] op_sel_hi:[1,0]
	v_pk_mul_f32 v[18:19], v[66:67], v[18:19] op_sel_hi:[1,0]
	v_pk_mul_f32 v[28:29], v[4:5], v[28:29]
	v_pk_mul_f32 v[20:21], v[14:15], v[20:21]
	v_pk_mul_f32 v[18:19], v[16:17], v[18:19]
	v_cvt_pk_bf16_f32 v26, v26, v27
	v_cvt_pk_bf16_f32 v27, v28, v29
	v_cvt_pk_bf16_f32 v20, v20, v21
	v_cvt_pk_bf16_f32 v21, v18, v19
	v_cmp_lt_i32_e32 vcc, s38, v34
	global_store_dwordx2 v[36:37], v[26:27], off offset:-3588
	global_store_dwordx2 v[36:37], v[20:21], off offset:-4
	v_lshl_add_u64 v[36:37], v[36:37], 0, s[10:11]
	s_or_b64 s[8:9], vcc, s[8:9]
	s_andn2_b64 exec, exec, s[8:9]
	s_cbranch_execnz .LBB0_17
